# v43 + write-through (sc1) on the final-norm pass-B output stores
# baseline (speedup 1.0000x reference)
; #define FN_LOAD(vv, row) do { _Pragma("unroll") for (int j = 0; j < 2; ++j) { const u32x4 w_ = *(const u32x4*)(XB + (size_t)(row) * DM + 8 * lane + 512 * j); vv[j][0] = bf4_to_f32((u32x2){w_.x, w_.y}); vv[j][1] = bf4_to_f32((u32x2){w_.z, w_.w}); } } while (0)
; __device__ __forceinline__ void final_norm(const Params& P, const XcdBarrier& xbar, int lane, int wave) {
;     ...
;     for (int row = gw; row < 16384; row += NGW) { f32x4 v[2][2]; FN_LOAD(v, row); FN_STORE(v, row); }
;     f32x4 vc[8][2][2];
; #pragma unroll
;     for (int k = 0; k < 8; ++k) { const int row = 16384 + gw + k * NGW; if (row < MLAT) FN_LOAD(vc[k], row); }
;     xcd_barrier(xbar);
; #pragma unroll
;     for (int k = 0; k < 8; ++k) { const int row = 16384 + gw + k * NGW; if (row < MLAT) FN_STORE(vc[k], row); }
.LBB0_154:
	s_or_b64 exec, exec, s[28:29]
	s_waitcnt lgkmcnt(0)
	v_lshlrev_b32_e32 v0, 2, v221
	v_xor_b32_e32 v139, 4, v0
	v_xor_b32_e32 v138, 8, v0
	v_xor_b32_e32 v137, 16, v0
	v_xor_b32_e32 v136, 32, v0
	v_xor_b32_e32 v13, 64, v0
	v_xor_b32_e32 v9, 0x80, v0
	s_and_b64 vcc, exec, s[54:55]
	s_barrier
	s_cbranch_vccz .LBB0_156
	v_pk_mul_f32 v[140:141], v[134:135], v[134:135]
	v_pk_mul_f32 v[142:143], v[132:133], v[132:133]
	v_mul_f32_e32 v0, v124, v124
	v_pk_mov_b32 v[144:145], v[142:143], v[140:141] op_sel:[1,0]
	v_mov_b32_e32 v143, v141
	v_pk_add_f32 v[140:141], v[144:145], v[142:143]
	v_pk_mul_f32 v[142:143], v[130:131], v[130:131]
	v_pk_mul_f32 v[144:145], v[128:129], v[128:129]
	v_pk_add_f32 v[140:141], v[140:141], v[140:141] op_sel_hi:[0,1]
	v_pk_mov_b32 v[146:147], v[144:145], v[142:143] op_sel:[1,0]
	v_mov_b32_e32 v145, v143
	v_pk_add_f32 v[142:143], v[146:147], v[144:145]
	v_pk_fma_f32 v[144:145], v[124:125], v[124:125], v[0:1] op_sel_hi:[1,1,0]
	v_mul_f32_e32 v0, v126, v126
	v_pk_add_f32 v[142:143], v[142:143], v[142:143] op_sel_hi:[0,1]
	v_pk_fma_f32 v[146:147], v[126:127], v[126:127], v[0:1] op_sel_hi:[1,1,0]
	v_mul_f32_e32 v144, v120, v120
	v_mul_f32_e32 v146, v121, v121
	v_mul_f32_e32 v142, v122, v122
	v_mul_f32_e32 v140, v123, v123
	v_pk_add_f32 v[144:145], v[144:145], v[146:147]
	v_pk_add_f32 v[140:141], v[142:143], v[140:141]
	s_mov_b64 s[12:13], s[50:51]
	v_pk_add_f32 v[140:141], v[144:145], v[140:141]
	s_mov_b64 s[22:23], s[52:53]
	v_add_f32_e32 v0, v140, v141
	ds_bpermute_b32 v140, v139, v0
	v_readlane_b32 s48, v251, 10
	v_lshlrev_b32_e32 v144, 2, v5
	v_readlane_b32 s60, v251, 22
	v_readlane_b32 s61, v251, 23
	s_waitcnt lgkmcnt(0)
	v_add_f32_e32 v0, v0, v140
	ds_bpermute_b32 v140, v138, v0
	s_ashr_i32 s65, s64, 31
	s_lshl_b64 s[28:29], s[64:65], 12
	v_readlane_b32 s62, v251, 24
	v_readlane_b32 s63, v251, 25
	s_waitcnt lgkmcnt(0)
	v_add_f32_e32 v0, v0, v140
	ds_bpermute_b32 v140, v137, v0
	s_add_u32 s28, s62, s28
	s_addc_u32 s29, s63, s29
	v_readlane_b32 s50, v251, 12
	v_readlane_b32 s51, v251, 13
	s_waitcnt lgkmcnt(0)
	v_add_f32_e32 v0, v0, v140
	ds_bpermute_b32 v140, v136, v0
	v_readlane_b32 s52, v251, 14
	v_readlane_b32 s53, v251, 15
	s_mov_b64 s[52:53], s[22:23]
	s_mov_b64 s[50:51], s[12:13]
	s_waitcnt lgkmcnt(0)
	v_add_f32_e32 v0, v0, v140
	ds_bpermute_b32 v140, v13, v0
	v_readlane_b32 s49, v251, 11
	v_readlane_b32 s54, v251, 16
	v_readlane_b32 s55, v251, 17
	v_readlane_b32 s56, v251, 18
	s_waitcnt lgkmcnt(0)
	v_add_f32_e32 v0, v0, v140
	ds_bpermute_b32 v140, v9, v0
	v_readlane_b32 s57, v251, 19
	v_readlane_b32 s58, v251, 20
	v_readlane_b32 s59, v251, 21
	s_waitcnt lgkmcnt(0)
	v_add_f32_e32 v0, v0, v140
	v_fmamk_f32 v0, v0, 0x3a800000, v194
	v_cmp_gt_f32_e32 vcc, s10, v0
	v_mul_f32_e32 v140, 0x4b800000, v0
	s_nop 0
	v_cndmask_b32_e32 v0, v0, v140, vcc
	v_rsq_f32_e32 v0, v0
	s_nop 0
	v_mul_f32_e32 v140, 0x45800000, v0
	v_cndmask_b32_e32 v0, v0, v140, vcc
	v_pk_mul_f32 v[140:141], v[132:133], v[0:1] op_sel_hi:[1,0]
	v_pk_mul_f32 v[142:143], v[134:135], v[0:1] op_sel_hi:[1,0]
	global_load_dwordx4 v[132:135], v144, s[60:61]
	s_waitcnt vmcnt(0)
	v_pk_mul_f32 v[134:135], v[134:135], v[142:143]
	v_pk_mul_f32 v[132:133], v[132:133], v[140:141]
	global_store_dwordx4 v144, v[132:135], s[28:29] sc1
	s_nop 1
	v_pk_mul_f32 v[132:133], v[130:131], v[0:1] op_sel_hi:[1,0]
	v_pk_mul_f32 v[134:135], v[128:129], v[0:1] op_sel_hi:[1,0]
	global_load_dwordx4 v[128:131], v144, s[60:61] offset:16
	s_waitcnt vmcnt(0)
	v_pk_mul_f32 v[128:129], v[128:129], v[134:135]
	v_pk_mul_f32 v[130:131], v[130:131], v[132:133]
	global_store_dwordx4 v144, v[128:131], s[28:29] offset:16 sc1
	s_nop 1
	v_pk_mul_f32 v[128:129], v[126:127], v[0:1] op_sel_hi:[1,0]
	v_pk_mul_f32 v[130:131], v[124:125], v[0:1] op_sel_hi:[1,0]
	global_load_dwordx4 v[124:127], v144, s[60:61] offset:2048
	s_waitcnt vmcnt(0)
	v_pk_mul_f32 v[124:125], v[124:125], v[130:131]
	v_pk_mul_f32 v[126:127], v[126:127], v[128:129]
	global_store_dwordx4 v144, v[124:127], s[28:29] offset:2048 sc1
	s_nop 1
	v_pk_mul_f32 v[124:125], v[122:123], v[0:1] op_sel_hi:[1,0]
	v_pk_mul_f32 v[126:127], v[120:121], v[0:1] op_sel_hi:[1,0]
	global_load_dwordx4 v[120:123], v144, s[60:61] offset:2064
	s_waitcnt vmcnt(0)
	v_pk_mul_f32 v[120:121], v[120:121], v[126:127]
	v_pk_mul_f32 v[122:123], v[122:123], v[124:125]
	global_store_dwordx4 v144, v[120:123], s[28:29] offset:2064 sc1
; #define FN_LOAD(vv, row) do { _Pragma("unroll") for (int j = 0; j < 2; ++j) { const u32x4 w_ = *(const u32x4*)(XB + (size_t)(row) * DM + 8 * lane + 512 * j); vv[j][0] = bf4_to_f32((u32x2){w_.x, w_.y}); vv[j][1] = bf4_to_f32((u32x2){w_.z, w_.w}); } } while (0)
; __device__ __forceinline__ void final_norm(const Params& P, const XcdBarrier& xbar, int lane, int wave) {
;     ...
;     for (int row = gw; row < 16384; row += NGW) { f32x4 v[2][2]; FN_LOAD(v, row); FN_STORE(v, row); }
;     f32x4 vc[8][2][2];
; #pragma unroll
;     for (int k = 0; k < 8; ++k) { const int row = 16384 + gw + k * NGW; if (row < MLAT) FN_LOAD(vc[k], row); }
;     xcd_barrier(xbar);
; #pragma unroll
;     for (int k = 0; k < 8; ++k) { const int row = 16384 + gw + k * NGW; if (row < MLAT) FN_STORE(vc[k], row); }
.LBB0_156:
	s_andn2_b64 vcc, exec, s[52:53]
	s_cbranch_vccnz .LBB0_158
	s_mov_b64 s[12:13], s[50:51]
	v_readlane_b32 s48, v251, 10
	v_lshlrev_b32_e32 v140, 2, v5
	v_readlane_b32 s60, v251, 22
	v_readlane_b32 s61, v251, 23
	v_pk_mul_f32 v[124:125], v[118:119], v[118:119]
	v_pk_mul_f32 v[126:127], v[116:117], v[116:117]
	v_pk_mul_f32 v[128:129], v[114:115], v[114:115]
	v_pk_mul_f32 v[130:131], v[112:113], v[112:113]
	v_pk_mov_b32 v[134:135], v[126:127], v[124:125] op_sel:[1,0]
	global_load_dwordx4 v[120:123], v140, s[60:61]
	v_mov_b32_e32 v127, v125
	v_pk_mov_b32 v[124:125], v[130:131], v[128:129] op_sel:[1,0]
	v_mov_b32_e32 v131, v129
	v_mul_f32_e32 v0, v108, v108
	v_mul_f32_e32 v132, v110, v110
	v_pk_add_f32 v[126:127], v[134:135], v[126:127]
	v_pk_add_f32 v[124:125], v[124:125], v[130:131]
	v_pk_fma_f32 v[128:129], v[108:109], v[108:109], v[0:1] op_sel_hi:[1,1,0]
	v_pk_fma_f32 v[132:133], v[110:111], v[110:111], v[132:133] op_sel_hi:[1,1,0]
	v_pk_add_f32 v[126:127], v[126:127], v[126:127] op_sel_hi:[0,1]
	v_pk_add_f32 v[124:125], v[124:125], v[124:125] op_sel_hi:[0,1]
	v_mul_f32_e32 v128, v104, v104
	v_mul_f32_e32 v132, v105, v105
	v_mul_f32_e32 v124, v106, v106
	v_mul_f32_e32 v126, v107, v107
	v_pk_add_f32 v[128:129], v[128:129], v[132:133]
	v_pk_add_f32 v[124:125], v[124:125], v[126:127]
	v_readlane_b32 s50, v251, 12
	v_pk_add_f32 v[124:125], v[128:129], v[124:125]
	v_readlane_b32 s51, v251, 13
	v_add_f32_e32 v0, v124, v125
	ds_bpermute_b32 v124, v139, v0
	s_ashr_i32 s9, s8, 31
	v_readlane_b32 s62, v251, 24
	s_mov_b64 s[50:51], s[12:13]
	s_lshl_b64 s[12:13], s[8:9], 12
	s_waitcnt lgkmcnt(0)
	v_add_f32_e32 v0, v0, v124
	ds_bpermute_b32 v124, v138, v0
	v_readlane_b32 s63, v251, 25
	s_add_u32 s12, s62, s12
	s_addc_u32 s13, s63, s13
	v_readlane_b32 s49, v251, 11
	s_waitcnt lgkmcnt(0)
	v_add_f32_e32 v0, v0, v124
	ds_bpermute_b32 v124, v137, v0
	v_readlane_b32 s52, v251, 14
	v_readlane_b32 s53, v251, 15
	v_readlane_b32 s54, v251, 16
	v_readlane_b32 s55, v251, 17
	s_waitcnt lgkmcnt(0)
	v_add_f32_e32 v0, v0, v124
	ds_bpermute_b32 v124, v136, v0
	v_readlane_b32 s56, v251, 18
	v_readlane_b32 s57, v251, 19
	v_readlane_b32 s58, v251, 20
	v_readlane_b32 s59, v251, 21
	s_waitcnt lgkmcnt(0)
	v_add_f32_e32 v0, v0, v124
	ds_bpermute_b32 v124, v13, v0
	s_waitcnt lgkmcnt(0)
	v_add_f32_e32 v0, v0, v124
	ds_bpermute_b32 v124, v9, v0
	s_waitcnt lgkmcnt(0)
	v_add_f32_e32 v0, v0, v124
	v_fmamk_f32 v0, v0, 0x3a800000, v194
	v_mul_f32_e32 v124, 0x4b800000, v0
	v_cmp_gt_f32_e32 vcc, s10, v0
	s_nop 1
	v_cndmask_b32_e32 v0, v0, v124, vcc
	v_rsq_f32_e32 v0, v0
	s_nop 0
	v_mul_f32_e32 v124, 0x45800000, v0
	v_cndmask_b32_e32 v0, v0, v124, vcc
	v_pk_mul_f32 v[116:117], v[116:117], v[0:1] op_sel_hi:[1,0]
	v_pk_mul_f32 v[118:119], v[118:119], v[0:1] op_sel_hi:[1,0]
	v_pk_mul_f32 v[114:115], v[114:115], v[0:1] op_sel_hi:[1,0]
	v_pk_mul_f32 v[112:113], v[112:113], v[0:1] op_sel_hi:[1,0]
	v_pk_mul_f32 v[110:111], v[110:111], v[0:1] op_sel_hi:[1,0]
	v_pk_mul_f32 v[108:109], v[108:109], v[0:1] op_sel_hi:[1,0]
	v_pk_mul_f32 v[106:107], v[106:107], v[0:1] op_sel_hi:[1,0]
	v_pk_mul_f32 v[104:105], v[104:105], v[0:1] op_sel_hi:[1,0]
	s_waitcnt vmcnt(0)
	v_pk_mul_f32 v[118:119], v[122:123], v[118:119]
	v_pk_mul_f32 v[116:117], v[120:121], v[116:117]
	global_store_dwordx4 v140, v[116:119], s[12:13] sc1
	global_load_dwordx4 v[116:119], v140, s[60:61] offset:16
	s_waitcnt vmcnt(0)
	v_pk_mul_f32 v[112:113], v[116:117], v[112:113]
	v_pk_mul_f32 v[114:115], v[118:119], v[114:115]
	global_store_dwordx4 v140, v[112:115], s[12:13] offset:16 sc1
	global_load_dwordx4 v[112:115], v140, s[60:61] offset:2048
	s_waitcnt vmcnt(0)
	v_pk_mul_f32 v[108:109], v[112:113], v[108:109]
	v_pk_mul_f32 v[110:111], v[114:115], v[110:111]
	global_store_dwordx4 v140, v[108:111], s[12:13] offset:2048 sc1
	global_load_dwordx4 v[108:111], v140, s[60:61] offset:2064
	s_waitcnt vmcnt(0)
	v_pk_mul_f32 v[104:105], v[108:109], v[104:105]
	v_pk_mul_f32 v[106:107], v[110:111], v[106:107]
	global_store_dwordx4 v140, v[104:107], s[12:13] offset:2064 sc1
.LBB0_158:
	v_readlane_b32 s64, v253, 54
	s_andn2_b64 vcc, exec, s[50:51]
	v_readlane_b32 s65, v253, 55
	v_readlane_b32 s66, v253, 56
	v_readlane_b32 s67, v253, 57
	s_cbranch_vccnz .LBB0_160
; #define FN_LOAD(vv, row) do { _Pragma("unroll") for (int j = 0; j < 2; ++j) { const u32x4 w_ = *(const u32x4*)(XB + (size_t)(row) * DM + 8 * lane + 512 * j); vv[j][0] = bf4_to_f32((u32x2){w_.x, w_.y}); vv[j][1] = bf4_to_f32((u32x2){w_.z, w_.w}); } } while (0)
; __device__ __forceinline__ void final_norm(const Params& P, const XcdBarrier& xbar, int lane, int wave) {
;     ...
;     for (int row = gw; row < 16384; row += NGW) { f32x4 v[2][2]; FN_LOAD(v, row); FN_STORE(v, row); }
;     f32x4 vc[8][2][2];
; #pragma unroll
;     for (int k = 0; k < 8; ++k) { const int row = 16384 + gw + k * NGW; if (row < MLAT) FN_LOAD(vc[k], row); }
;     xcd_barrier(xbar);
; #pragma unroll
;     for (int k = 0; k < 8; ++k) { const int row = 16384 + gw + k * NGW; if (row < MLAT) FN_STORE(vc[k], row); }
	v_readlane_b32 s48, v251, 10
	v_lshlrev_b32_e32 v120, 2, v5
	v_readlane_b32 s60, v251, 22
	v_readlane_b32 s61, v251, 23
	v_pk_mul_f32 v[108:109], v[102:103], v[102:103]
	v_pk_mul_f32 v[110:111], v[100:101], v[100:101]
	v_pk_mul_f32 v[112:113], v[98:99], v[98:99]
	v_pk_mul_f32 v[114:115], v[96:97], v[96:97]
	v_pk_mov_b32 v[118:119], v[110:111], v[108:109] op_sel:[1,0]
	global_load_dwordx4 v[104:107], v120, s[60:61]
	v_mov_b32_e32 v111, v109
	v_pk_mov_b32 v[108:109], v[114:115], v[112:113] op_sel:[1,0]
	v_mov_b32_e32 v115, v113
	v_mul_f32_e32 v0, v92, v92
	v_mul_f32_e32 v116, v94, v94
	v_pk_add_f32 v[110:111], v[118:119], v[110:111]
	v_pk_add_f32 v[108:109], v[108:109], v[114:115]
	v_pk_fma_f32 v[112:113], v[92:93], v[92:93], v[0:1] op_sel_hi:[1,1,0]
	v_pk_fma_f32 v[116:117], v[94:95], v[94:95], v[116:117] op_sel_hi:[1,1,0]
	v_pk_add_f32 v[110:111], v[110:111], v[110:111] op_sel_hi:[0,1]
	v_pk_add_f32 v[108:109], v[108:109], v[108:109] op_sel_hi:[0,1]
	v_mul_f32_e32 v112, v88, v88
	v_mul_f32_e32 v116, v89, v89
	v_mul_f32_e32 v108, v90, v90
	v_mul_f32_e32 v110, v91, v91
	v_pk_add_f32 v[112:113], v[112:113], v[116:117]
	v_pk_add_f32 v[108:109], v[108:109], v[110:111]
	s_ashr_i32 s45, s44, 31
	v_pk_add_f32 v[108:109], v[112:113], v[108:109]
	v_readlane_b32 s62, v251, 24
	v_add_f32_e32 v0, v108, v109
	ds_bpermute_b32 v108, v139, v0
	s_lshl_b64 s[12:13], s[44:45], 12
	v_readlane_b32 s63, v251, 25
	s_add_u32 s12, s62, s12
	s_addc_u32 s13, s63, s13
	s_waitcnt lgkmcnt(0)
	v_add_f32_e32 v0, v0, v108
	ds_bpermute_b32 v108, v138, v0
	v_readlane_b32 s49, v251, 11
	v_readlane_b32 s50, v251, 12
	v_readlane_b32 s51, v251, 13
	v_readlane_b32 s52, v251, 14
	s_waitcnt lgkmcnt(0)
	v_add_f32_e32 v0, v0, v108
	ds_bpermute_b32 v108, v137, v0
	v_readlane_b32 s53, v251, 15
	v_readlane_b32 s54, v251, 16
	v_readlane_b32 s55, v251, 17
	v_readlane_b32 s56, v251, 18
	s_waitcnt lgkmcnt(0)
	v_add_f32_e32 v0, v0, v108
	ds_bpermute_b32 v108, v136, v0
	v_readlane_b32 s57, v251, 19
	v_readlane_b32 s58, v251, 20
	v_readlane_b32 s59, v251, 21
	s_waitcnt lgkmcnt(0)
	v_add_f32_e32 v0, v0, v108
	ds_bpermute_b32 v108, v13, v0
	s_waitcnt lgkmcnt(0)
	v_add_f32_e32 v0, v0, v108
	ds_bpermute_b32 v108, v9, v0
	s_waitcnt lgkmcnt(0)
	v_add_f32_e32 v0, v0, v108
	v_fmamk_f32 v0, v0, 0x3a800000, v194
	v_mul_f32_e32 v108, 0x4b800000, v0
	v_cmp_gt_f32_e32 vcc, s10, v0
	s_nop 1
	v_cndmask_b32_e32 v0, v0, v108, vcc
	v_rsq_f32_e32 v0, v0
	s_nop 0
	v_mul_f32_e32 v108, 0x45800000, v0
	v_cndmask_b32_e32 v0, v0, v108, vcc
	v_pk_mul_f32 v[100:101], v[100:101], v[0:1] op_sel_hi:[1,0]
	v_pk_mul_f32 v[102:103], v[102:103], v[0:1] op_sel_hi:[1,0]
	v_pk_mul_f32 v[98:99], v[98:99], v[0:1] op_sel_hi:[1,0]
	v_pk_mul_f32 v[96:97], v[96:97], v[0:1] op_sel_hi:[1,0]
	v_pk_mul_f32 v[94:95], v[94:95], v[0:1] op_sel_hi:[1,0]
	v_pk_mul_f32 v[92:93], v[92:93], v[0:1] op_sel_hi:[1,0]
	v_pk_mul_f32 v[90:91], v[90:91], v[0:1] op_sel_hi:[1,0]
	v_pk_mul_f32 v[88:89], v[88:89], v[0:1] op_sel_hi:[1,0]
	s_waitcnt vmcnt(0)
	v_pk_mul_f32 v[102:103], v[106:107], v[102:103]
	v_pk_mul_f32 v[100:101], v[104:105], v[100:101]
	global_store_dwordx4 v120, v[100:103], s[12:13] sc1
	global_load_dwordx4 v[100:103], v120, s[60:61] offset:16
	s_waitcnt vmcnt(0)
	v_pk_mul_f32 v[96:97], v[100:101], v[96:97]
	v_pk_mul_f32 v[98:99], v[102:103], v[98:99]
	global_store_dwordx4 v120, v[96:99], s[12:13] offset:16 sc1
	global_load_dwordx4 v[96:99], v120, s[60:61] offset:2048
	s_waitcnt vmcnt(0)
	v_pk_mul_f32 v[92:93], v[96:97], v[92:93]
	v_pk_mul_f32 v[94:95], v[98:99], v[94:95]
	global_store_dwordx4 v120, v[92:95], s[12:13] offset:2048 sc1
	global_load_dwordx4 v[92:95], v120, s[60:61] offset:2064
	s_waitcnt vmcnt(0)
	v_pk_mul_f32 v[88:89], v[92:93], v[88:89]
	v_pk_mul_f32 v[90:91], v[94:95], v[90:91]
	global_store_dwordx4 v120, v[88:91], s[12:13] offset:2064 sc1
.LBB0_160:
	v_readlane_b32 s8, v253, 60
	v_readlane_b32 s9, v253, 61
	s_andn2_b64 vcc, exec, s[8:9]
	s_cbranch_vccnz .LBB0_162
	v_readlane_b32 s48, v251, 10
	v_lshlrev_b32_e32 v104, 2, v5
	v_readlane_b32 s60, v251, 22
	v_readlane_b32 s61, v251, 23
	v_pk_mul_f32 v[92:93], v[86:87], v[86:87]
	v_pk_mul_f32 v[94:95], v[84:85], v[84:85]
	v_pk_mul_f32 v[96:97], v[82:83], v[82:83]
	v_pk_mul_f32 v[98:99], v[80:81], v[80:81]
	v_pk_mov_b32 v[102:103], v[94:95], v[92:93] op_sel:[1,0]
	global_load_dwordx4 v[88:91], v104, s[60:61]
	v_mov_b32_e32 v95, v93
	v_pk_mov_b32 v[92:93], v[98:99], v[96:97] op_sel:[1,0]
	v_mov_b32_e32 v99, v97
	v_mul_f32_e32 v0, v76, v76
	v_mul_f32_e32 v100, v78, v78
	v_pk_add_f32 v[94:95], v[102:103], v[94:95]
	v_pk_add_f32 v[92:93], v[92:93], v[98:99]
	v_pk_fma_f32 v[96:97], v[76:77], v[76:77], v[0:1] op_sel_hi:[1,1,0]
	v_pk_fma_f32 v[100:101], v[78:79], v[78:79], v[100:101] op_sel_hi:[1,1,0]
	v_pk_add_f32 v[94:95], v[94:95], v[94:95] op_sel_hi:[0,1]
	v_pk_add_f32 v[92:93], v[92:93], v[92:93] op_sel_hi:[0,1]
	v_mul_f32_e32 v96, v72, v72
	v_mul_f32_e32 v100, v73, v73
	v_mul_f32_e32 v92, v74, v74
	v_mul_f32_e32 v94, v75, v75
	v_pk_add_f32 v[96:97], v[96:97], v[100:101]
	v_pk_add_f32 v[92:93], v[92:93], v[94:95]
	s_ashr_i32 s85, s84, 31
	v_pk_add_f32 v[92:93], v[96:97], v[92:93]
	v_readlane_b32 s62, v251, 24
	v_add_f32_e32 v0, v92, v93
	ds_bpermute_b32 v92, v139, v0
	s_lshl_b64 s[12:13], s[84:85], 12
	v_readlane_b32 s63, v251, 25
	s_add_u32 s12, s62, s12
	s_addc_u32 s13, s63, s13
	s_waitcnt lgkmcnt(0)
	v_add_f32_e32 v0, v0, v92
	ds_bpermute_b32 v92, v138, v0
	v_readlane_b32 s49, v251, 11
	v_readlane_b32 s50, v251, 12
	v_readlane_b32 s51, v251, 13
	v_readlane_b32 s52, v251, 14
	s_waitcnt lgkmcnt(0)
; #define FN_LOAD(vv, row) do { _Pragma("unroll") for (int j = 0; j < 2; ++j) { const u32x4 w_ = *(const u32x4*)(XB + (size_t)(row) * DM + 8 * lane + 512 * j); vv[j][0] = bf4_to_f32((u32x2){w_.x, w_.y}); vv[j][1] = bf4_to_f32((u32x2){w_.z, w_.w}); } } while (0)
; __device__ __forceinline__ void final_norm(const Params& P, const XcdBarrier& xbar, int lane, int wave) {
;     ...
;     for (int row = gw; row < 16384; row += NGW) { f32x4 v[2][2]; FN_LOAD(v, row); FN_STORE(v, row); }
;     f32x4 vc[8][2][2];
; #pragma unroll
;     for (int k = 0; k < 8; ++k) { const int row = 16384 + gw + k * NGW; if (row < MLAT) FN_LOAD(vc[k], row); }
;     xcd_barrier(xbar);
; #pragma unroll
;     for (int k = 0; k < 8; ++k) { const int row = 16384 + gw + k * NGW; if (row < MLAT) FN_STORE(vc[k], row); }
	v_add_f32_e32 v0, v0, v92
	ds_bpermute_b32 v92, v137, v0
	v_readlane_b32 s53, v251, 15
	v_readlane_b32 s54, v251, 16
	v_readlane_b32 s55, v251, 17
	v_readlane_b32 s56, v251, 18
	s_waitcnt lgkmcnt(0)
	v_add_f32_e32 v0, v0, v92
	ds_bpermute_b32 v92, v136, v0
	v_readlane_b32 s57, v251, 19
	v_readlane_b32 s58, v251, 20
	v_readlane_b32 s59, v251, 21
	s_waitcnt lgkmcnt(0)
	v_add_f32_e32 v0, v0, v92
	ds_bpermute_b32 v92, v13, v0
	s_waitcnt lgkmcnt(0)
	v_add_f32_e32 v0, v0, v92
	ds_bpermute_b32 v92, v9, v0
	s_waitcnt lgkmcnt(0)
	v_add_f32_e32 v0, v0, v92
	v_fmamk_f32 v0, v0, 0x3a800000, v194
	v_mul_f32_e32 v92, 0x4b800000, v0
	v_cmp_gt_f32_e32 vcc, s10, v0
	s_nop 1
	v_cndmask_b32_e32 v0, v0, v92, vcc
	v_rsq_f32_e32 v0, v0
	s_nop 0
	v_mul_f32_e32 v92, 0x45800000, v0
	v_cndmask_b32_e32 v0, v0, v92, vcc
	v_pk_mul_f32 v[84:85], v[84:85], v[0:1] op_sel_hi:[1,0]
	v_pk_mul_f32 v[86:87], v[86:87], v[0:1] op_sel_hi:[1,0]
	v_pk_mul_f32 v[82:83], v[82:83], v[0:1] op_sel_hi:[1,0]
	v_pk_mul_f32 v[80:81], v[80:81], v[0:1] op_sel_hi:[1,0]
	v_pk_mul_f32 v[78:79], v[78:79], v[0:1] op_sel_hi:[1,0]
	v_pk_mul_f32 v[76:77], v[76:77], v[0:1] op_sel_hi:[1,0]
	v_pk_mul_f32 v[74:75], v[74:75], v[0:1] op_sel_hi:[1,0]
	v_pk_mul_f32 v[72:73], v[72:73], v[0:1] op_sel_hi:[1,0]
	s_waitcnt vmcnt(0)
	v_pk_mul_f32 v[86:87], v[90:91], v[86:87]
	v_pk_mul_f32 v[84:85], v[88:89], v[84:85]
	global_store_dwordx4 v104, v[84:87], s[12:13] sc1
	global_load_dwordx4 v[84:87], v104, s[60:61] offset:16
	s_waitcnt vmcnt(0)
	v_pk_mul_f32 v[80:81], v[84:85], v[80:81]
	v_pk_mul_f32 v[82:83], v[86:87], v[82:83]
	global_store_dwordx4 v104, v[80:83], s[12:13] offset:16 sc1
	global_load_dwordx4 v[80:83], v104, s[60:61] offset:2048
	s_waitcnt vmcnt(0)
	v_pk_mul_f32 v[76:77], v[80:81], v[76:77]
	v_pk_mul_f32 v[78:79], v[82:83], v[78:79]
	global_store_dwordx4 v104, v[76:79], s[12:13] offset:2048 sc1
	global_load_dwordx4 v[76:79], v104, s[60:61] offset:2064
	s_waitcnt vmcnt(0)
	v_pk_mul_f32 v[72:73], v[76:77], v[72:73]
	v_pk_mul_f32 v[74:75], v[78:79], v[74:75]
	global_store_dwordx4 v104, v[72:75], s[12:13] offset:2064 sc1
.LBB0_162:
	v_readlane_b32 s8, v253, 62
	v_readlane_b32 s9, v253, 63
	s_andn2_b64 vcc, exec, s[8:9]
	s_mov_b32 s44, s14
	s_cbranch_vccnz .LBB0_164
	v_readlane_b32 s48, v251, 10
	v_lshlrev_b32_e32 v88, 2, v5
	v_readlane_b32 s60, v251, 22
	v_readlane_b32 s61, v251, 23
	v_pk_mul_f32 v[76:77], v[70:71], v[70:71]
	v_pk_mul_f32 v[78:79], v[68:69], v[68:69]
	v_pk_mul_f32 v[80:81], v[66:67], v[66:67]
	v_pk_mul_f32 v[82:83], v[64:65], v[64:65]
	v_pk_mov_b32 v[86:87], v[78:79], v[76:77] op_sel:[1,0]
	global_load_dwordx4 v[72:75], v88, s[60:61]
	v_mov_b32_e32 v79, v77
	v_pk_mov_b32 v[76:77], v[82:83], v[80:81] op_sel:[1,0]
	v_mov_b32_e32 v83, v81
	v_mul_f32_e32 v0, v60, v60
	v_mul_f32_e32 v84, v62, v62
	v_pk_add_f32 v[78:79], v[86:87], v[78:79]
	v_pk_add_f32 v[76:77], v[76:77], v[82:83]
	v_pk_fma_f32 v[80:81], v[60:61], v[60:61], v[0:1] op_sel_hi:[1,1,0]
	v_pk_fma_f32 v[84:85], v[62:63], v[62:63], v[84:85] op_sel_hi:[1,1,0]
	v_pk_add_f32 v[78:79], v[78:79], v[78:79] op_sel_hi:[0,1]
	v_pk_add_f32 v[76:77], v[76:77], v[76:77] op_sel_hi:[0,1]
	v_mul_f32_e32 v80, v56, v56
	v_mul_f32_e32 v84, v57, v57
	v_mul_f32_e32 v76, v58, v58
	v_mul_f32_e32 v78, v59, v59
	v_pk_add_f32 v[80:81], v[80:81], v[84:85]
	v_pk_add_f32 v[76:77], v[76:77], v[78:79]
	s_ashr_i32 s41, s40, 31
	v_pk_add_f32 v[76:77], v[80:81], v[76:77]
	v_readlane_b32 s62, v251, 24
	v_add_f32_e32 v0, v76, v77
	ds_bpermute_b32 v76, v139, v0
	s_lshl_b64 s[12:13], s[40:41], 12
	v_readlane_b32 s63, v251, 25
	s_add_u32 s12, s62, s12
	s_addc_u32 s13, s63, s13
	s_waitcnt lgkmcnt(0)
	v_add_f32_e32 v0, v0, v76
	ds_bpermute_b32 v76, v138, v0
	v_readlane_b32 s49, v251, 11
	v_readlane_b32 s50, v251, 12
	v_readlane_b32 s51, v251, 13
	v_readlane_b32 s52, v251, 14
	s_waitcnt lgkmcnt(0)
	v_add_f32_e32 v0, v0, v76
	ds_bpermute_b32 v76, v137, v0
	v_readlane_b32 s53, v251, 15
	v_readlane_b32 s54, v251, 16
	v_readlane_b32 s55, v251, 17
	v_readlane_b32 s56, v251, 18
	s_waitcnt lgkmcnt(0)
	v_add_f32_e32 v0, v0, v76
	ds_bpermute_b32 v76, v136, v0
	v_readlane_b32 s57, v251, 19
	v_readlane_b32 s58, v251, 20
	v_readlane_b32 s59, v251, 21
	s_waitcnt lgkmcnt(0)
	v_add_f32_e32 v0, v0, v76
	ds_bpermute_b32 v76, v13, v0
	s_waitcnt lgkmcnt(0)
	v_add_f32_e32 v0, v0, v76
	ds_bpermute_b32 v76, v9, v0
	s_waitcnt lgkmcnt(0)
	v_add_f32_e32 v0, v0, v76
	v_fmamk_f32 v0, v0, 0x3a800000, v194
	v_mul_f32_e32 v76, 0x4b800000, v0
	v_cmp_gt_f32_e32 vcc, s10, v0
	s_nop 1
	v_cndmask_b32_e32 v0, v0, v76, vcc
	v_rsq_f32_e32 v0, v0
	s_nop 0
	v_mul_f32_e32 v76, 0x45800000, v0
	v_cndmask_b32_e32 v0, v0, v76, vcc
	v_pk_mul_f32 v[68:69], v[68:69], v[0:1] op_sel_hi:[1,0]
	v_pk_mul_f32 v[70:71], v[70:71], v[0:1] op_sel_hi:[1,0]
	v_pk_mul_f32 v[66:67], v[66:67], v[0:1] op_sel_hi:[1,0]
	v_pk_mul_f32 v[64:65], v[64:65], v[0:1] op_sel_hi:[1,0]
	v_pk_mul_f32 v[62:63], v[62:63], v[0:1] op_sel_hi:[1,0]
	v_pk_mul_f32 v[60:61], v[60:61], v[0:1] op_sel_hi:[1,0]
	v_pk_mul_f32 v[58:59], v[58:59], v[0:1] op_sel_hi:[1,0]
	v_pk_mul_f32 v[56:57], v[56:57], v[0:1] op_sel_hi:[1,0]
	s_waitcnt vmcnt(0)
	v_pk_mul_f32 v[70:71], v[74:75], v[70:71]
	v_pk_mul_f32 v[68:69], v[72:73], v[68:69]
	global_store_dwordx4 v88, v[68:71], s[12:13] sc1
	global_load_dwordx4 v[68:71], v88, s[60:61] offset:16
	s_waitcnt vmcnt(0)
	v_pk_mul_f32 v[64:65], v[68:69], v[64:65]
	v_pk_mul_f32 v[66:67], v[70:71], v[66:67]
	global_store_dwordx4 v88, v[64:67], s[12:13] offset:16 sc1
	global_load_dwordx4 v[64:67], v88, s[60:61] offset:2048
	s_waitcnt vmcnt(0)
	v_pk_mul_f32 v[60:61], v[64:65], v[60:61]
	v_pk_mul_f32 v[62:63], v[66:67], v[62:63]
	global_store_dwordx4 v88, v[60:63], s[12:13] offset:2048 sc1
	global_load_dwordx4 v[60:63], v88, s[60:61] offset:2064
	s_waitcnt vmcnt(0)
	v_pk_mul_f32 v[56:57], v[60:61], v[56:57]
	v_pk_mul_f32 v[58:59], v[62:63], v[58:59]
	global_store_dwordx4 v88, v[56:59], s[12:13] offset:2064 sc1
; #define FN_LOAD(vv, row) do { _Pragma("unroll") for (int j = 0; j < 2; ++j) { const u32x4 w_ = *(const u32x4*)(XB + (size_t)(row) * DM + 8 * lane + 512 * j); vv[j][0] = bf4_to_f32((u32x2){w_.x, w_.y}); vv[j][1] = bf4_to_f32((u32x2){w_.z, w_.w}); } } while (0)
; __device__ __forceinline__ void final_norm(const Params& P, const XcdBarrier& xbar, int lane, int wave) {
;     ...
;     for (int row = gw; row < 16384; row += NGW) { f32x4 v[2][2]; FN_LOAD(v, row); FN_STORE(v, row); }
;     f32x4 vc[8][2][2];
; #pragma unroll
;     for (int k = 0; k < 8; ++k) { const int row = 16384 + gw + k * NGW; if (row < MLAT) FN_LOAD(vc[k], row); }
;     xcd_barrier(xbar);
; #pragma unroll
;     for (int k = 0; k < 8; ++k) { const int row = 16384 + gw + k * NGW; if (row < MLAT) FN_STORE(vc[k], row); }
.LBB0_164:
	v_readlane_b32 s8, v250, 0
	v_readlane_b32 s9, v250, 1
	s_andn2_b64 vcc, exec, s[8:9]
	s_cbranch_vccnz .LBB0_166
	v_readlane_b32 s48, v251, 10
	v_lshlrev_b32_e32 v72, 2, v5
	v_readlane_b32 s60, v251, 22
	v_readlane_b32 s61, v251, 23
	v_pk_mul_f32 v[60:61], v[54:55], v[54:55]
	v_pk_mul_f32 v[62:63], v[52:53], v[52:53]
	v_pk_mul_f32 v[64:65], v[50:51], v[50:51]
	v_pk_mul_f32 v[66:67], v[48:49], v[48:49]
	v_pk_mov_b32 v[70:71], v[62:63], v[60:61] op_sel:[1,0]
	global_load_dwordx4 v[56:59], v72, s[60:61]
	v_mov_b32_e32 v63, v61
	v_pk_mov_b32 v[60:61], v[66:67], v[64:65] op_sel:[1,0]
	v_mov_b32_e32 v67, v65
	s_waitcnt vmcnt(5)
	v_mul_f32_e32 v0, v44, v44
	v_mul_f32_e32 v68, v46, v46
	v_pk_add_f32 v[62:63], v[70:71], v[62:63]
	v_pk_add_f32 v[60:61], v[60:61], v[66:67]
	v_pk_fma_f32 v[64:65], v[44:45], v[44:45], v[0:1] op_sel_hi:[1,1,0]
	v_pk_fma_f32 v[68:69], v[46:47], v[46:47], v[68:69] op_sel_hi:[1,1,0]
	v_pk_add_f32 v[62:63], v[62:63], v[62:63] op_sel_hi:[0,1]
	v_pk_add_f32 v[60:61], v[60:61], v[60:61] op_sel_hi:[0,1]
	v_mul_f32_e32 v64, v40, v40
	v_mul_f32_e32 v68, v41, v41
	v_mul_f32_e32 v60, v42, v42
	v_mul_f32_e32 v62, v43, v43
	v_pk_add_f32 v[64:65], v[64:65], v[68:69]
	v_pk_add_f32 v[60:61], v[60:61], v[62:63]
	s_ashr_i32 s27, s26, 31
	v_pk_add_f32 v[60:61], v[64:65], v[60:61]
	v_readlane_b32 s62, v251, 24
	v_add_f32_e32 v0, v60, v61
	ds_bpermute_b32 v60, v139, v0
	s_lshl_b64 s[12:13], s[26:27], 12
	v_readlane_b32 s63, v251, 25
	s_add_u32 s12, s62, s12
	s_addc_u32 s13, s63, s13
	s_waitcnt lgkmcnt(0)
	v_add_f32_e32 v0, v0, v60
	ds_bpermute_b32 v60, v138, v0
	v_readlane_b32 s49, v251, 11
	v_readlane_b32 s50, v251, 12
	v_readlane_b32 s51, v251, 13
	v_readlane_b32 s52, v251, 14
	s_waitcnt lgkmcnt(0)
	v_add_f32_e32 v0, v0, v60
	ds_bpermute_b32 v60, v137, v0
	v_readlane_b32 s53, v251, 15
	v_readlane_b32 s54, v251, 16
	v_readlane_b32 s55, v251, 17
	v_readlane_b32 s56, v251, 18
	s_waitcnt lgkmcnt(0)
	v_add_f32_e32 v0, v0, v60
	ds_bpermute_b32 v60, v136, v0
	v_readlane_b32 s57, v251, 19
	v_readlane_b32 s58, v251, 20
	v_readlane_b32 s59, v251, 21
	s_waitcnt lgkmcnt(0)
	v_add_f32_e32 v0, v0, v60
	ds_bpermute_b32 v60, v13, v0
	s_waitcnt lgkmcnt(0)
	v_add_f32_e32 v0, v0, v60
	ds_bpermute_b32 v60, v9, v0
	s_waitcnt lgkmcnt(0)
	v_add_f32_e32 v0, v0, v60
	v_fmamk_f32 v0, v0, 0x3a800000, v194
	v_mul_f32_e32 v60, 0x4b800000, v0
	v_cmp_gt_f32_e32 vcc, s10, v0
	s_nop 1
	v_cndmask_b32_e32 v0, v0, v60, vcc
	v_rsq_f32_e32 v0, v0
	s_nop 0
	v_mul_f32_e32 v60, 0x45800000, v0
	v_cndmask_b32_e32 v0, v0, v60, vcc
	v_pk_mul_f32 v[52:53], v[52:53], v[0:1] op_sel_hi:[1,0]
	v_pk_mul_f32 v[54:55], v[54:55], v[0:1] op_sel_hi:[1,0]
	v_pk_mul_f32 v[50:51], v[50:51], v[0:1] op_sel_hi:[1,0]
	v_pk_mul_f32 v[48:49], v[48:49], v[0:1] op_sel_hi:[1,0]
	v_pk_mul_f32 v[46:47], v[46:47], v[0:1] op_sel_hi:[1,0]
	v_pk_mul_f32 v[44:45], v[44:45], v[0:1] op_sel_hi:[1,0]
	v_pk_mul_f32 v[42:43], v[42:43], v[0:1] op_sel_hi:[1,0]
	v_pk_mul_f32 v[40:41], v[40:41], v[0:1] op_sel_hi:[1,0]
	s_waitcnt vmcnt(0)
	v_pk_mul_f32 v[54:55], v[58:59], v[54:55]
	v_pk_mul_f32 v[52:53], v[56:57], v[52:53]
	global_store_dwordx4 v72, v[52:55], s[12:13] sc1
	global_load_dwordx4 v[52:55], v72, s[60:61] offset:16
	s_waitcnt vmcnt(0)
	v_pk_mul_f32 v[48:49], v[52:53], v[48:49]
	v_pk_mul_f32 v[50:51], v[54:55], v[50:51]
	global_store_dwordx4 v72, v[48:51], s[12:13] offset:16 sc1
	global_load_dwordx4 v[48:51], v72, s[60:61] offset:2048
	s_waitcnt vmcnt(0)
	v_pk_mul_f32 v[44:45], v[48:49], v[44:45]
	v_pk_mul_f32 v[46:47], v[50:51], v[46:47]
	global_store_dwordx4 v72, v[44:47], s[12:13] offset:2048 sc1
	global_load_dwordx4 v[44:47], v72, s[60:61] offset:2064
	s_waitcnt vmcnt(0)
	v_pk_mul_f32 v[40:41], v[44:45], v[40:41]
	v_pk_mul_f32 v[42:43], v[46:47], v[42:43]
	global_store_dwordx4 v72, v[40:43], s[12:13] offset:2064 sc1
.LBB0_166:
	v_readlane_b32 s8, v250, 2
	v_readlane_b32 s9, v250, 3
	s_andn2_b64 vcc, exec, s[8:9]
	s_cbranch_vccnz .LBB0_168
	v_readlane_b32 s48, v251, 10
	v_lshlrev_b32_e32 v56, 2, v5
	v_readlane_b32 s60, v251, 22
	v_readlane_b32 s61, v251, 23
	s_waitcnt vmcnt(4)
	v_pk_mul_f32 v[44:45], v[38:39], v[38:39]
	v_pk_mul_f32 v[46:47], v[36:37], v[36:37]
	v_pk_mul_f32 v[48:49], v[34:35], v[34:35]
	v_pk_mul_f32 v[50:51], v[32:33], v[32:33]
	v_pk_mov_b32 v[54:55], v[46:47], v[44:45] op_sel:[1,0]
	global_load_dwordx4 v[40:43], v56, s[60:61]
	v_mov_b32_e32 v47, v45
	v_pk_mov_b32 v[44:45], v[50:51], v[48:49] op_sel:[1,0]
	v_mov_b32_e32 v51, v49
	v_mul_f32_e32 v0, v28, v28
	v_mul_f32_e32 v52, v30, v30
	v_pk_add_f32 v[46:47], v[54:55], v[46:47]
	v_pk_add_f32 v[44:45], v[44:45], v[50:51]
	v_pk_fma_f32 v[48:49], v[28:29], v[28:29], v[0:1] op_sel_hi:[1,1,0]
	v_pk_fma_f32 v[52:53], v[30:31], v[30:31], v[52:53] op_sel_hi:[1,1,0]
	v_pk_add_f32 v[46:47], v[46:47], v[46:47] op_sel_hi:[0,1]
	v_pk_add_f32 v[44:45], v[44:45], v[44:45] op_sel_hi:[0,1]
	v_mul_f32_e32 v48, v24, v24
	v_mul_f32_e32 v52, v25, v25
	v_mul_f32_e32 v44, v26, v26
	v_mul_f32_e32 v46, v27, v27
	v_pk_add_f32 v[48:49], v[48:49], v[52:53]
	v_pk_add_f32 v[44:45], v[44:45], v[46:47]
	s_ashr_i32 s3, s2, 31
	v_pk_add_f32 v[44:45], v[48:49], v[44:45]
	v_readlane_b32 s62, v251, 24
	v_add_f32_e32 v0, v44, v45
	ds_bpermute_b32 v44, v139, v0
	s_lshl_b64 s[2:3], s[2:3], 12
	v_readlane_b32 s63, v251, 25
	s_add_u32 s2, s62, s2
	s_addc_u32 s3, s63, s3
	s_waitcnt lgkmcnt(0)
	v_add_f32_e32 v0, v0, v44
	ds_bpermute_b32 v44, v138, v0
	v_readlane_b32 s49, v251, 11
	v_readlane_b32 s50, v251, 12
	v_readlane_b32 s51, v251, 13
	v_readlane_b32 s52, v251, 14
	s_waitcnt lgkmcnt(0)
; #define FN_LOAD(vv, row) do { _Pragma("unroll") for (int j = 0; j < 2; ++j) { const u32x4 w_ = *(const u32x4*)(XB + (size_t)(row) * DM + 8 * lane + 512 * j); vv[j][0] = bf4_to_f32((u32x2){w_.x, w_.y}); vv[j][1] = bf4_to_f32((u32x2){w_.z, w_.w}); } } while (0)
; __device__ __forceinline__ void final_norm(const Params& P, const XcdBarrier& xbar, int lane, int wave) {
;     ...
;     for (int row = gw; row < 16384; row += NGW) { f32x4 v[2][2]; FN_LOAD(v, row); FN_STORE(v, row); }
;     f32x4 vc[8][2][2];
; #pragma unroll
;     for (int k = 0; k < 8; ++k) { const int row = 16384 + gw + k * NGW; if (row < MLAT) FN_LOAD(vc[k], row); }
;     xcd_barrier(xbar);
; #pragma unroll
;     for (int k = 0; k < 8; ++k) { const int row = 16384 + gw + k * NGW; if (row < MLAT) FN_STORE(vc[k], row); }
	v_add_f32_e32 v0, v0, v44
	ds_bpermute_b32 v44, v137, v0
	v_readlane_b32 s53, v251, 15
	v_readlane_b32 s54, v251, 16
	v_readlane_b32 s55, v251, 17
	v_readlane_b32 s56, v251, 18
	s_waitcnt lgkmcnt(0)
	v_add_f32_e32 v0, v0, v44
	ds_bpermute_b32 v44, v136, v0
	v_readlane_b32 s57, v251, 19
	v_readlane_b32 s58, v251, 20
	v_readlane_b32 s59, v251, 21
	s_waitcnt lgkmcnt(0)
	v_add_f32_e32 v0, v0, v44
	ds_bpermute_b32 v44, v13, v0
	s_waitcnt lgkmcnt(0)
	v_add_f32_e32 v0, v0, v44
	ds_bpermute_b32 v44, v9, v0
	s_waitcnt lgkmcnt(0)
	v_add_f32_e32 v0, v0, v44
	v_fmamk_f32 v0, v0, 0x3a800000, v194
	v_mul_f32_e32 v44, 0x4b800000, v0
	v_cmp_gt_f32_e32 vcc, s10, v0
	s_nop 1
	v_cndmask_b32_e32 v0, v0, v44, vcc
	v_rsq_f32_e32 v0, v0
	s_nop 0
	v_mul_f32_e32 v44, 0x45800000, v0
	v_cndmask_b32_e32 v0, v0, v44, vcc
	v_pk_mul_f32 v[36:37], v[36:37], v[0:1] op_sel_hi:[1,0]
	v_pk_mul_f32 v[38:39], v[38:39], v[0:1] op_sel_hi:[1,0]
	v_pk_mul_f32 v[34:35], v[34:35], v[0:1] op_sel_hi:[1,0]
	v_pk_mul_f32 v[32:33], v[32:33], v[0:1] op_sel_hi:[1,0]
	v_pk_mul_f32 v[30:31], v[30:31], v[0:1] op_sel_hi:[1,0]
	v_pk_mul_f32 v[28:29], v[28:29], v[0:1] op_sel_hi:[1,0]
	v_pk_mul_f32 v[26:27], v[26:27], v[0:1] op_sel_hi:[1,0]
	v_pk_mul_f32 v[24:25], v[24:25], v[0:1] op_sel_hi:[1,0]
	s_waitcnt vmcnt(0)
	v_pk_mul_f32 v[38:39], v[42:43], v[38:39]
	v_pk_mul_f32 v[36:37], v[40:41], v[36:37]
	global_store_dwordx4 v56, v[36:39], s[2:3] sc1
	global_load_dwordx4 v[36:39], v56, s[60:61] offset:16
	s_waitcnt vmcnt(0)
	v_pk_mul_f32 v[32:33], v[36:37], v[32:33]
	v_pk_mul_f32 v[34:35], v[38:39], v[34:35]
	global_store_dwordx4 v56, v[32:35], s[2:3] offset:16 sc1
	global_load_dwordx4 v[32:35], v56, s[60:61] offset:2048
	s_waitcnt vmcnt(0)
	v_pk_mul_f32 v[28:29], v[32:33], v[28:29]
	v_pk_mul_f32 v[30:31], v[34:35], v[30:31]
	global_store_dwordx4 v56, v[28:31], s[2:3] offset:2048 sc1
	global_load_dwordx4 v[28:31], v56, s[60:61] offset:2064
	s_waitcnt vmcnt(0)
	v_pk_mul_f32 v[24:25], v[28:29], v[24:25]
	v_pk_mul_f32 v[26:27], v[30:31], v[26:27]
	global_store_dwordx4 v56, v[24:27], s[2:3] offset:2064 sc1
.LBB0_168:
	s_andn2_b64 vcc, exec, s[42:43]
	s_cbranch_vccnz .LBB0_170
	v_readlane_b32 s48, v251, 10
	v_lshlrev_b32_e32 v5, 2, v5
	v_readlane_b32 s60, v251, 22
	v_readlane_b32 s61, v251, 23
	s_waitcnt vmcnt(8)
	v_pk_mul_f32 v[28:29], v[22:23], v[22:23]
	s_waitcnt vmcnt(7)
	v_pk_mul_f32 v[30:31], v[20:21], v[20:21]
	v_pk_mul_f32 v[32:33], v[18:19], v[18:19]
	s_waitcnt vmcnt(6)
	v_pk_mul_f32 v[34:35], v[16:17], v[16:17]
	s_waitcnt vmcnt(5)
	v_pk_mov_b32 v[38:39], v[30:31], v[28:29] op_sel:[1,0]
	global_load_dwordx4 v[24:27], v5, s[60:61]
	v_mov_b32_e32 v31, v29
	v_pk_mov_b32 v[28:29], v[34:35], v[32:33] op_sel:[1,0]
	v_mov_b32_e32 v35, v33
	v_mul_f32_e32 v0, v10, v10
	v_mul_f32_e32 v36, v14, v14
	v_pk_add_f32 v[30:31], v[38:39], v[30:31]
	v_pk_add_f32 v[28:29], v[28:29], v[34:35]
	v_pk_fma_f32 v[32:33], v[10:11], v[10:11], v[0:1] op_sel_hi:[1,1,0]
	v_pk_fma_f32 v[36:37], v[14:15], v[14:15], v[36:37] op_sel_hi:[1,1,0]
	v_pk_add_f32 v[30:31], v[30:31], v[30:31] op_sel_hi:[0,1]
	v_pk_add_f32 v[28:29], v[28:29], v[28:29] op_sel_hi:[0,1]
	v_mul_f32_e32 v32, v2, v2
	v_mul_f32_e32 v36, v3, v3
	v_mul_f32_e32 v28, v6, v6
	v_mul_f32_e32 v30, v7, v7
	v_pk_add_f32 v[32:33], v[32:33], v[36:37]
	v_pk_add_f32 v[28:29], v[28:29], v[30:31]
	s_ashr_i32 s1, s0, 31
	v_pk_add_f32 v[28:29], v[32:33], v[28:29]
	v_readlane_b32 s62, v251, 24
	v_add_f32_e32 v0, v28, v29
	ds_bpermute_b32 v28, v139, v0
	s_lshl_b64 s[0:1], s[0:1], 12
	v_readlane_b32 s63, v251, 25
	s_add_u32 s0, s62, s0
	s_addc_u32 s1, s63, s1
	s_waitcnt lgkmcnt(0)
	v_add_f32_e32 v0, v0, v28
	ds_bpermute_b32 v28, v138, v0
	v_readlane_b32 s49, v251, 11
	v_readlane_b32 s50, v251, 12
	v_readlane_b32 s51, v251, 13
	v_readlane_b32 s52, v251, 14
	s_waitcnt lgkmcnt(0)
	v_add_f32_e32 v0, v0, v28
	ds_bpermute_b32 v28, v137, v0
	v_readlane_b32 s53, v251, 15
	v_readlane_b32 s54, v251, 16
	v_readlane_b32 s55, v251, 17
	v_readlane_b32 s56, v251, 18
	s_waitcnt lgkmcnt(0)
	v_add_f32_e32 v0, v0, v28
	ds_bpermute_b32 v28, v136, v0
	v_readlane_b32 s57, v251, 19
	v_readlane_b32 s58, v251, 20
	v_readlane_b32 s59, v251, 21
	s_waitcnt lgkmcnt(0)
	v_add_f32_e32 v0, v0, v28
	ds_bpermute_b32 v13, v13, v0
	s_waitcnt lgkmcnt(0)
	v_add_f32_e32 v0, v0, v13
	ds_bpermute_b32 v9, v9, v0
	s_waitcnt lgkmcnt(0)
	v_add_f32_e32 v0, v0, v9
	v_fmamk_f32 v0, v0, 0x3a800000, v194
	v_mul_f32_e32 v9, 0x4b800000, v0
	v_cmp_gt_f32_e32 vcc, s10, v0
	s_nop 1
	v_cndmask_b32_e32 v0, v0, v9, vcc
	v_rsq_f32_e32 v0, v0
	s_nop 0
	v_mul_f32_e32 v9, 0x45800000, v0
	v_cndmask_b32_e32 v0, v0, v9, vcc
	v_pk_mul_f32 v[20:21], v[20:21], v[0:1] op_sel_hi:[1,0]
	v_pk_mul_f32 v[22:23], v[22:23], v[0:1] op_sel_hi:[1,0]
	v_pk_mul_f32 v[18:19], v[18:19], v[0:1] op_sel_hi:[1,0]
	v_pk_mul_f32 v[16:17], v[16:17], v[0:1] op_sel_hi:[1,0]
	v_pk_mul_f32 v[10:11], v[10:11], v[0:1] op_sel_hi:[1,0]
	v_pk_mul_f32 v[6:7], v[6:7], v[0:1] op_sel_hi:[1,0]
	v_pk_mul_f32 v[2:3], v[2:3], v[0:1] op_sel_hi:[1,0]
	s_waitcnt vmcnt(0)
	v_pk_mul_f32 v[22:23], v[26:27], v[22:23]
	v_pk_mul_f32 v[20:21], v[24:25], v[20:21]
	global_store_dwordx4 v5, v[20:23], s[0:1] sc1
	global_load_dwordx4 v[20:23], v5, s[60:61] offset:16
	s_waitcnt vmcnt(0)
	v_pk_mul_f32 v[16:17], v[20:21], v[16:17]
	v_pk_mul_f32 v[18:19], v[22:23], v[18:19]
	global_store_dwordx4 v5, v[16:19], s[0:1] offset:16 sc1
	global_load_dwordx4 v[16:19], v5, s[60:61] offset:2048
	v_pk_mul_f32 v[20:21], v[14:15], v[0:1] op_sel_hi:[1,0]
	s_waitcnt vmcnt(0)
	v_pk_mul_f32 v[14:15], v[16:17], v[10:11]
	v_pk_mul_f32 v[16:17], v[18:19], v[20:21]
	global_store_dwordx4 v5, v[14:17], s[0:1] offset:2048 sc1
	global_load_dwordx4 v[14:17], v5, s[60:61] offset:2064
	s_waitcnt vmcnt(0)
	v_pk_mul_f32 v[14:15], v[14:15], v[2:3]
	v_pk_mul_f32 v[16:17], v[16:17], v[6:7]
	global_store_dwordx4 v5, v[14:17], s[0:1] offset:2064 sc1
